# attention unit map: the 32 CUs of an XCD work on one head at a time (head 4*xcd+j for unit j, halves of the XCD alternate the long/short unit) instead of two heads side by side
# baseline (speedup 1.0000x reference)
.LBB0_26:
	s_cmp_ge_i32 s20, s12
	s_cselect_b64 s[16:17], -1, 0
	s_mov_b64 s[0:1], -1
	s_and_b64 vcc, exec, s[16:17]
	s_cbranch_vccnz .LBB0_28
	s_cmpk_lg_i32 s33, 0x100
	s_cbranch_scc1 .Lunit27_orig
	s_lshr_b32 s0, s83, 5
	s_lshl_b32 s0, s0, 2
	s_add_i32 s18, s0, s20
	s_lshr_b32 s40, s18, 3
	s_lshl_b32 s0, s83, 8
	s_and_b32 s0, s0, 0xf00
	s_lshr_b32 s1, s83, 4
	s_xor_b32 s1, s1, s20
	s_and_b32 s1, s1, 1
	s_branch .Lunit27_sel
.Lunit27_orig:
	s_lshr_b32 s0, s20, 1
	s_mul_i32 s0, s0, s33
	s_add_i32 s0, s0, s83
	s_lshr_b32 s18, s0, 4
	s_ashr_i32 s40, s0, 7
	s_lshl_b32 s0, s0, 8
	s_and_b32 s0, s0, 0xf00
	s_and_b32 s1, s20, 1
.Lunit27_sel:
	s_xor_b32 s6, s0, 0x1f00
	s_cmp_eq_u32 s1, 0
	s_cselect_b32 s0, s6, s0
	s_or_b32 s44, s0, 0x80
	s_mov_b64 s[0:1], 0

; #define ATT_UNIT_PARAMS(j, B_, H_, R_, S_) do { if ((j) < nmain) { const int it = vcu + ((j) >> 1) * G, bh = it >> 4, s_ = it & 15; B_ = bh >> 3; H_ = bh & 7; R_ = 128 + 256 * (((j) & 1) ? s_ : 31 - s_); S_ = false; } \
;         else { const int it = (G == 256) ? sp0 : vcu + ((j) - nmain) * G; B_ = it >> 3; H_ = it & 7; R_ = 0; S_ = true; } } while (0)
; __device__ __forceinline__ void phase_attn(const Args& a, int l, LAS unsigned char* lds, int vcu, int G, int wv) {
;     ...
;     const int nun = nmain + nspec;
;     for (int j = 0; j < nun; ++j) {
;         int b, h, R0, nb = 0, nh = 0, nR0 = 0; bool special, nsp = false;
;         ATT_UNIT_PARAMS(j, b, h, R0, special);
;         const bool hasn = j + 1 < nun;
;         if (hasn) ATT_UNIT_PARAMS(j + 1, nb, nh, nR0, nsp);
.LBB0_33:
	s_andn2_b64 vcc, exec, s[0:1]
	s_cbranch_vccnz .LBB0_35
	s_cmpk_lg_i32 s33, 0x100
	s_cbranch_scc1 .Lunit34_orig
	s_lshr_b32 s0, s83, 5
	s_lshl_b32 s0, s0, 2
	s_add_i32 s0, s0, s56
	s_lshr_b32 s57, s0, 3
	s_and_b32 s58, s0, 7
	s_lshl_b32 s0, s83, 8
	s_and_b32 s0, s0, 0xf00
	s_lshr_b32 s1, s83, 4
	s_xor_b32 s1, s1, s56
	s_and_b32 s1, s1, 1
	s_xor_b32 s1, s1, 1
	s_branch .Lunit34_sel
.Lunit34_orig:
	s_lshr_b32 s0, s56, 1
	s_mul_i32 s0, s0, s33
	s_add_i32 s0, s0, s83
	s_ashr_i32 s57, s0, 7
	s_bfe_u32 s58, s0, 0x30004
	s_lshl_b32 s0, s0, 8
	s_and_b32 s0, s0, 0xf00
	s_and_b32 s1, s20, 1
.Lunit34_sel:
	s_xor_b32 s19, s0, 0x1f00
	s_cmp_eq_u32 s1, 0
	s_cselect_b32 s0, s0, s19
	s_or_b32 s62, s0, 0x80
